# FFN gate/up phases: per-row scale loads for the epilogue issued inside the unit's last MMA block
# baseline (speedup 1.0000x reference)
.LBB0_783:
	s_ashr_i32 s23, s22, 31
	s_lshl_b64 s[26:27], s[22:23], 19
	s_add_u32 s26, s43, s26
	s_addc_u32 s27, s44, s27
	s_and_b64 s[28:29], s[4:5], exec
	s_cselect_b32 s23, s27, s37
	s_cselect_b32 s31, s26, s36
	s_ashr_i32 s25, s24, 31
	s_lshl_b64 s[28:29], s[24:25], 19
	s_add_u32 s28, s45, s28
	s_addc_u32 s29, s46, s29
	s_and_b64 s[40:41], s[4:5], exec
	s_cselect_b32 s25, s29, s39
	s_cselect_b32 s62, s28, s38
	s_add_u32 s36, s36, 0x40080
	s_addc_u32 s37, s37, 0
	s_add_u32 s63, s38, 0x100
	v_mov_b32_e32 v0, 0
	s_addc_u32 s64, s39, 0
	s_mov_b32 s65, -2
	v_mov_b32_e32 v1, v0
	v_mov_b32_e32 v2, v0
	v_mov_b32_e32 v3, v0
	v_mov_b32_e32 v4, v0
	v_mov_b32_e32 v5, v0
	v_mov_b32_e32 v6, v0
	v_mov_b32_e32 v7, v0
	v_mov_b32_e32 v16, v0
	v_mov_b32_e32 v17, v0
	v_mov_b32_e32 v18, v0
	v_mov_b32_e32 v19, v0
	v_mov_b32_e32 v20, v0
	v_mov_b32_e32 v21, v0
	v_mov_b32_e32 v22, v0
	v_mov_b32_e32 v23, v0
	v_mov_b32_e32 v32, v0
	v_mov_b32_e32 v33, v0
	v_mov_b32_e32 v34, v0
	v_mov_b32_e32 v35, v0
	v_mov_b32_e32 v36, v0
	v_mov_b32_e32 v37, v0
	v_mov_b32_e32 v38, v0
	v_mov_b32_e32 v39, v0
	v_mov_b32_e32 v48, v0
	v_mov_b32_e32 v49, v0
	v_mov_b32_e32 v50, v0
	v_mov_b32_e32 v51, v0
	v_mov_b32_e32 v52, v0
	v_mov_b32_e32 v53, v0
	v_mov_b32_e32 v54, v0
	v_mov_b32_e32 v55, v0
	v_mov_b32_e32 v8, v0
	v_mov_b32_e32 v9, v0
	v_mov_b32_e32 v10, v0
	v_mov_b32_e32 v11, v0
	v_mov_b32_e32 v12, v0
	v_mov_b32_e32 v13, v0
	v_mov_b32_e32 v14, v0
	v_mov_b32_e32 v15, v0
	v_mov_b32_e32 v24, v0
	v_mov_b32_e32 v25, v0
	v_mov_b32_e32 v26, v0
	v_mov_b32_e32 v27, v0
	v_mov_b32_e32 v28, v0
	v_mov_b32_e32 v29, v0
	v_mov_b32_e32 v30, v0
	v_mov_b32_e32 v31, v0
	v_mov_b32_e32 v40, v0
	v_mov_b32_e32 v41, v0
	v_mov_b32_e32 v42, v0
	v_mov_b32_e32 v43, v0
	v_mov_b32_e32 v44, v0
	v_mov_b32_e32 v45, v0
	v_mov_b32_e32 v46, v0
	v_mov_b32_e32 v47, v0
	v_mov_b32_e32 v56, v0
	v_mov_b32_e32 v57, v0
	v_mov_b32_e32 v58, v0
	v_mov_b32_e32 v59, v0
	v_mov_b32_e32 v60, v0
	v_mov_b32_e32 v61, v0
	v_mov_b32_e32 v62, v0
	v_mov_b32_e32 v63, v0
	v_mov_b32_e32 v64, v0
	v_mov_b32_e32 v65, v0
	v_mov_b32_e32 v66, v0
	v_mov_b32_e32 v67, v0
	v_mov_b32_e32 v68, v0
	v_mov_b32_e32 v69, v0
	v_mov_b32_e32 v70, v0
	v_mov_b32_e32 v71, v0
	v_mov_b32_e32 v80, v0
	v_mov_b32_e32 v81, v0
	v_mov_b32_e32 v82, v0
	v_mov_b32_e32 v83, v0
	v_mov_b32_e32 v84, v0
	v_mov_b32_e32 v85, v0
	v_mov_b32_e32 v86, v0
	v_mov_b32_e32 v87, v0
	v_mov_b32_e32 v96, v0
	v_mov_b32_e32 v97, v0
	v_mov_b32_e32 v98, v0
	v_mov_b32_e32 v99, v0
	v_mov_b32_e32 v100, v0
	v_mov_b32_e32 v101, v0
	v_mov_b32_e32 v102, v0
	v_mov_b32_e32 v103, v0
	v_mov_b32_e32 v112, v0
	v_mov_b32_e32 v113, v0
	v_mov_b32_e32 v114, v0
	v_mov_b32_e32 v115, v0
	v_mov_b32_e32 v116, v0
	v_mov_b32_e32 v117, v0
	v_mov_b32_e32 v118, v0
	v_mov_b32_e32 v119, v0
	v_mov_b32_e32 v72, v0
	v_mov_b32_e32 v73, v0
	v_mov_b32_e32 v74, v0
	v_mov_b32_e32 v75, v0
	v_mov_b32_e32 v76, v0
	v_mov_b32_e32 v77, v0
	v_mov_b32_e32 v78, v0
	v_mov_b32_e32 v79, v0
	v_mov_b32_e32 v88, v0
	v_mov_b32_e32 v89, v0
	v_mov_b32_e32 v90, v0
	v_mov_b32_e32 v91, v0
	v_mov_b32_e32 v92, v0
	v_mov_b32_e32 v93, v0
	v_mov_b32_e32 v94, v0
	v_mov_b32_e32 v95, v0
	v_mov_b32_e32 v104, v0
	v_mov_b32_e32 v105, v0
	v_mov_b32_e32 v106, v0
	v_mov_b32_e32 v107, v0
	v_mov_b32_e32 v108, v0
	v_mov_b32_e32 v109, v0
	v_mov_b32_e32 v110, v0
	v_mov_b32_e32 v111, v0
	v_mov_b32_e32 v120, v0
	v_mov_b32_e32 v121, v0
	v_mov_b32_e32 v122, v0
	v_mov_b32_e32 v123, v0
	v_mov_b32_e32 v124, v0
	v_mov_b32_e32 v125, v0
	v_mov_b32_e32 v126, v0
	v_mov_b32_e32 v127, v0
	s_lshl_b32 s99, s30, 8
	s_add_i32 s99, s99, s56
	v_mbcnt_lo_u32_b32 v232, -1, 0
	v_mbcnt_hi_u32_b32 v232, -1, v232
	v_and_or_b32 v232, v232, 15, s99
	v_lshlrev_b32_e32 v232, 2, v232
.LBB0_784:
	ds_read_b128 v[144:147], v163
	ds_read_b128 v[148:151], v163 offset:1024
	ds_read_b128 v[152:155], v163 offset:2048
	ds_read_b128 v[156:159], v163 offset:3072
	ds_read_b128 v[168:171], v164
	ds_read_b128 v[172:175], v164 offset:1024
	ds_read_b128 v[176:179], v164 offset:2048
	ds_read_b128 v[180:183], v164 offset:3072
	s_add_u32 s38, s36, 0xfffc0080
	s_addc_u32 s39, s37, -1
	s_cmp_eq_u32 s65, 12
	s_cselect_b32 s41, s23, s39
	s_cselect_b32 s40, s31, s38
	s_cselect_b32 s39, s25, s64
	s_cselect_b32 s38, s62, s63
	v_lshl_add_u64 v[160:161], s[36:37], 0, v[136:137]
	s_add_i32 m0, s50, 0xc000
	ds_read_b128 v[184:187], v165
	ds_read_b128 v[188:191], v165 offset:1024
	ds_read_b128 v[192:195], v165 offset:2048
	ds_read_b128 v[196:199], v165 offset:3072
	ds_read_b128 v[200:203], v165 offset:4096
	ds_read_b128 v[204:207], v165 offset:5120
	ds_read_b128 v[208:211], v165 offset:6144
	ds_read_b128 v[212:215], v165 offset:7168
	global_load_lds_dwordx4 v[160:161], off
	v_lshl_add_u64 v[160:161], s[36:37], 0, v[138:139]
	s_add_i32 m0, s50, 0xe000
	s_nop 0
	global_load_lds_dwordx4 v[160:161], off
	s_waitcnt vmcnt(8)
	s_waitcnt lgkmcnt(0)
	s_barrier
	s_setprio 1
	s_waitcnt lgkmcnt(0)
	v_mfma_f32_16x16x32_bf16 v[124:127], v[144:147], v[184:187], v[124:127]
	v_mfma_f32_16x16x32_bf16 v[120:123], v[152:155], v[184:187], v[120:123]
	v_mfma_f32_16x16x32_bf16 v[108:111], v[144:147], v[192:195], v[108:111]
	v_mfma_f32_16x16x32_bf16 v[104:107], v[152:155], v[192:195], v[104:107]
	v_mfma_f32_16x16x32_bf16 v[92:95], v[144:147], v[200:203], v[92:95]
	v_mfma_f32_16x16x32_bf16 v[88:91], v[152:155], v[200:203], v[88:91]
	v_mfma_f32_16x16x32_bf16 v[76:79], v[144:147], v[208:211], v[76:79]
	v_mfma_f32_16x16x32_bf16 v[72:75], v[152:155], v[208:211], v[72:75]
	v_mfma_f32_16x16x32_bf16 v[124:127], v[148:151], v[188:191], v[124:127]
	v_mfma_f32_16x16x32_bf16 v[120:123], v[156:159], v[188:191], v[120:123]
	v_mfma_f32_16x16x32_bf16 v[108:111], v[148:151], v[196:199], v[108:111]
	v_mfma_f32_16x16x32_bf16 v[104:107], v[156:159], v[196:199], v[104:107]
	v_mfma_f32_16x16x32_bf16 v[92:95], v[148:151], v[204:207], v[92:95]
	v_mfma_f32_16x16x32_bf16 v[88:91], v[156:159], v[204:207], v[88:91]
	v_mfma_f32_16x16x32_bf16 v[76:79], v[148:151], v[212:215], v[76:79]
	v_mfma_f32_16x16x32_bf16 v[72:75], v[156:159], v[212:215], v[72:75]
	s_setprio 0
	s_setprio 1
	v_mfma_f32_16x16x32_bf16 v[116:119], v[168:171], v[184:187], v[116:119]
	v_mfma_f32_16x16x32_bf16 v[112:115], v[176:179], v[184:187], v[112:115]
	v_mfma_f32_16x16x32_bf16 v[100:103], v[168:171], v[192:195], v[100:103]
	v_mfma_f32_16x16x32_bf16 v[96:99], v[176:179], v[192:195], v[96:99]
	v_mfma_f32_16x16x32_bf16 v[84:87], v[168:171], v[200:203], v[84:87]
	v_mfma_f32_16x16x32_bf16 v[80:83], v[176:179], v[200:203], v[80:83]
	v_mfma_f32_16x16x32_bf16 v[68:71], v[168:171], v[208:211], v[68:71]
	v_mfma_f32_16x16x32_bf16 v[64:67], v[176:179], v[208:211], v[64:67]
	v_mfma_f32_16x16x32_bf16 v[116:119], v[172:175], v[188:191], v[116:119]
	v_mfma_f32_16x16x32_bf16 v[112:115], v[180:183], v[188:191], v[112:115]
	v_mfma_f32_16x16x32_bf16 v[100:103], v[172:175], v[196:199], v[100:103]
	v_mfma_f32_16x16x32_bf16 v[96:99], v[180:183], v[196:199], v[96:99]
	s_setprio 2
	s_barrier
	v_mfma_f32_16x16x32_bf16 v[84:87], v[172:175], v[204:207], v[84:87]
	v_mfma_f32_16x16x32_bf16 v[80:83], v[180:183], v[204:207], v[80:83]
	v_mfma_f32_16x16x32_bf16 v[68:71], v[172:175], v[212:215], v[68:71]
	v_mfma_f32_16x16x32_bf16 v[64:67], v[180:183], v[212:215], v[64:67]
	s_setprio 0
	s_add_i32 s66, s59, s47
	v_lshl_add_u64 v[160:161], s[38:39], 0, v[132:133]
	s_mov_b32 m0, s66
	ds_read_b128 v[184:187], v165 offset:16384
	ds_read_b128 v[188:191], v165 offset:17408
	ds_read_b128 v[192:195], v165 offset:18432
	ds_read_b128 v[196:199], v165 offset:19456
	ds_read_b128 v[200:203], v165 offset:20480
	ds_read_b128 v[204:207], v165 offset:21504
	ds_read_b128 v[208:211], v165 offset:22528
	ds_read_b128 v[212:215], v165 offset:23552
	global_load_lds_dwordx4 v[160:161], off
	s_add_i32 m0, s66, 0x2000
	s_add_u32 s66, s38, 0x40000
	v_lshl_add_u64 v[216:217], s[38:39], 0, v[128:129]
	s_addc_u32 s67, s39, 0
	s_add_i32 s68, s60, s47
	global_load_lds_dwordx4 v[216:217], off
	v_lshl_add_u64 v[218:219], s[66:67], 0, v[132:133]
	s_mov_b32 m0, s68
	v_lshl_add_u64 v[220:221], s[40:41], 0, v[130:131]
	global_load_lds_dwordx4 v[218:219], off
	v_lshl_add_u64 v[218:219], s[66:67], 0, v[128:129]
	s_add_i32 m0, s68, 0x2000
	s_nop 0
	global_load_lds_dwordx4 v[218:219], off
	v_lshl_add_u64 v[218:219], s[40:41], 0, v[134:135]
	s_mov_b32 m0, s50
	s_nop 0
	global_load_lds_dwordx4 v[218:219], off
	s_mov_b32 m0, s51
	s_nop 0
	global_load_lds_dwordx4 v[220:221], off
	s_waitcnt vmcnt(8)
	s_waitcnt lgkmcnt(0)
	s_barrier
	s_setprio 1
	s_waitcnt lgkmcnt(0)
	v_mfma_f32_16x16x32_bf16 v[60:63], v[144:147], v[184:187], v[60:63]
	v_mfma_f32_16x16x32_bf16 v[56:59], v[152:155], v[184:187], v[56:59]
	v_mfma_f32_16x16x32_bf16 v[44:47], v[144:147], v[192:195], v[44:47]
	v_mfma_f32_16x16x32_bf16 v[40:43], v[152:155], v[192:195], v[40:43]
	v_mfma_f32_16x16x32_bf16 v[28:31], v[144:147], v[200:203], v[28:31]
	v_mfma_f32_16x16x32_bf16 v[24:27], v[152:155], v[200:203], v[24:27]
	v_mfma_f32_16x16x32_bf16 v[12:15], v[144:147], v[208:211], v[12:15]
	v_mfma_f32_16x16x32_bf16 v[8:11], v[152:155], v[208:211], v[8:11]
	v_mfma_f32_16x16x32_bf16 v[60:63], v[148:151], v[188:191], v[60:63]
	v_mfma_f32_16x16x32_bf16 v[56:59], v[156:159], v[188:191], v[56:59]
	v_mfma_f32_16x16x32_bf16 v[44:47], v[148:151], v[196:199], v[44:47]
	v_mfma_f32_16x16x32_bf16 v[40:43], v[156:159], v[196:199], v[40:43]
	v_mfma_f32_16x16x32_bf16 v[28:31], v[148:151], v[204:207], v[28:31]
	v_mfma_f32_16x16x32_bf16 v[24:27], v[156:159], v[204:207], v[24:27]
	v_mfma_f32_16x16x32_bf16 v[12:15], v[148:151], v[212:215], v[12:15]
	v_mfma_f32_16x16x32_bf16 v[8:11], v[156:159], v[212:215], v[8:11]
	s_setprio 0
	s_setprio 1
	v_mfma_f32_16x16x32_bf16 v[52:55], v[168:171], v[184:187], v[52:55]
	v_mfma_f32_16x16x32_bf16 v[48:51], v[176:179], v[184:187], v[48:51]
	v_mfma_f32_16x16x32_bf16 v[36:39], v[168:171], v[192:195], v[36:39]
	v_mfma_f32_16x16x32_bf16 v[32:35], v[176:179], v[192:195], v[32:35]
	v_mfma_f32_16x16x32_bf16 v[20:23], v[168:171], v[200:203], v[20:23]
	v_mfma_f32_16x16x32_bf16 v[16:19], v[176:179], v[200:203], v[16:19]
	v_mfma_f32_16x16x32_bf16 v[4:7], v[168:171], v[208:211], v[4:7]
	v_mfma_f32_16x16x32_bf16 v[0:3], v[176:179], v[208:211], v[0:3]
	v_mfma_f32_16x16x32_bf16 v[52:55], v[172:175], v[188:191], v[52:55]
	v_mfma_f32_16x16x32_bf16 v[48:51], v[180:183], v[188:191], v[48:51]
	v_mfma_f32_16x16x32_bf16 v[36:39], v[172:175], v[196:199], v[36:39]
	v_mfma_f32_16x16x32_bf16 v[32:35], v[180:183], v[196:199], v[32:35]
	s_setprio 2
	s_barrier
	v_mfma_f32_16x16x32_bf16 v[20:23], v[172:175], v[204:207], v[20:23]
	v_mfma_f32_16x16x32_bf16 v[16:19], v[180:183], v[204:207], v[16:19]
	v_mfma_f32_16x16x32_bf16 v[4:7], v[172:175], v[212:215], v[4:7]
	v_mfma_f32_16x16x32_bf16 v[0:3], v[180:183], v[212:215], v[0:3]
	s_setprio 0
	s_add_i32 s66, 0, 0x18000
	s_add_i32 s67, 0, 0x1c000
	v_add_u32_e32 v156, s66, v162
	v_add_u32_e32 v167, s67, v162
	ds_read_b128 v[144:147], v156
	ds_read_b128 v[148:151], v156 offset:1024
	ds_read_b128 v[152:155], v156 offset:2048
	ds_read_b128 v[156:159], v156 offset:3072
	ds_read_b128 v[168:171], v167
	ds_read_b128 v[172:175], v167 offset:1024
	ds_read_b128 v[176:179], v167 offset:2048
	ds_read_b128 v[180:183], v167 offset:3072
	s_add_u32 s40, s40, 0x40000
	s_addc_u32 s41, s41, 0
	s_mov_b32 m0, s54
	v_lshl_add_u64 v[222:223], s[40:41], 0, v[134:135]
	ds_read_b128 v[184:187], v165 offset:32768
	ds_read_b128 v[188:191], v165 offset:33792
	ds_read_b128 v[192:195], v165 offset:34816
	ds_read_b128 v[196:199], v165 offset:35840
	ds_read_b128 v[200:203], v165 offset:36864
	ds_read_b128 v[204:207], v165 offset:37888
	ds_read_b128 v[208:211], v165 offset:38912
	ds_read_b128 v[212:215], v165 offset:39936
	global_load_lds_dwordx4 v[222:223], off
	v_lshl_add_u64 v[222:223], s[40:41], 0, v[130:131]
	s_mov_b32 m0, s55
	s_nop 0
	global_load_lds_dwordx4 v[222:223], off
	s_waitcnt vmcnt(8)
	s_waitcnt lgkmcnt(0)
	s_barrier
	s_setprio 1
	s_waitcnt lgkmcnt(0)
	v_mfma_f32_16x16x32_bf16 v[124:127], v[144:147], v[184:187], v[124:127]
	v_mfma_f32_16x16x32_bf16 v[120:123], v[152:155], v[184:187], v[120:123]
	v_mfma_f32_16x16x32_bf16 v[108:111], v[144:147], v[192:195], v[108:111]
	v_mfma_f32_16x16x32_bf16 v[104:107], v[152:155], v[192:195], v[104:107]
	v_mfma_f32_16x16x32_bf16 v[92:95], v[144:147], v[200:203], v[92:95]
	v_mfma_f32_16x16x32_bf16 v[88:91], v[152:155], v[200:203], v[88:91]
	v_mfma_f32_16x16x32_bf16 v[76:79], v[144:147], v[208:211], v[76:79]
	v_mfma_f32_16x16x32_bf16 v[72:75], v[152:155], v[208:211], v[72:75]
	v_mfma_f32_16x16x32_bf16 v[124:127], v[148:151], v[188:191], v[124:127]
	v_mfma_f32_16x16x32_bf16 v[120:123], v[156:159], v[188:191], v[120:123]
	v_mfma_f32_16x16x32_bf16 v[108:111], v[148:151], v[196:199], v[108:111]
	v_mfma_f32_16x16x32_bf16 v[104:107], v[156:159], v[196:199], v[104:107]
	v_mfma_f32_16x16x32_bf16 v[92:95], v[148:151], v[204:207], v[92:95]
	v_mfma_f32_16x16x32_bf16 v[88:91], v[156:159], v[204:207], v[88:91]
	v_mfma_f32_16x16x32_bf16 v[76:79], v[148:151], v[212:215], v[76:79]
	v_mfma_f32_16x16x32_bf16 v[72:75], v[156:159], v[212:215], v[72:75]
	s_setprio 0
	s_setprio 1
	v_mfma_f32_16x16x32_bf16 v[116:119], v[168:171], v[184:187], v[116:119]
	v_mfma_f32_16x16x32_bf16 v[112:115], v[176:179], v[184:187], v[112:115]
	v_mfma_f32_16x16x32_bf16 v[100:103], v[168:171], v[192:195], v[100:103]
	v_mfma_f32_16x16x32_bf16 v[96:99], v[176:179], v[192:195], v[96:99]
	v_mfma_f32_16x16x32_bf16 v[84:87], v[168:171], v[200:203], v[84:87]
	v_mfma_f32_16x16x32_bf16 v[80:83], v[176:179], v[200:203], v[80:83]
	v_mfma_f32_16x16x32_bf16 v[68:71], v[168:171], v[208:211], v[68:71]
	v_mfma_f32_16x16x32_bf16 v[64:67], v[176:179], v[208:211], v[64:67]
	v_mfma_f32_16x16x32_bf16 v[116:119], v[172:175], v[188:191], v[116:119]
	v_mfma_f32_16x16x32_bf16 v[112:115], v[180:183], v[188:191], v[112:115]
	v_mfma_f32_16x16x32_bf16 v[100:103], v[172:175], v[196:199], v[100:103]
	v_mfma_f32_16x16x32_bf16 v[96:99], v[180:183], v[196:199], v[96:99]
	s_setprio 2
	s_barrier
	v_mfma_f32_16x16x32_bf16 v[84:87], v[172:175], v[204:207], v[84:87]
	v_mfma_f32_16x16x32_bf16 v[80:83], v[180:183], v[204:207], v[80:83]
	v_mfma_f32_16x16x32_bf16 v[68:71], v[172:175], v[212:215], v[68:71]
	v_mfma_f32_16x16x32_bf16 v[64:67], v[180:183], v[212:215], v[64:67]
	s_setprio 0
	s_add_i32 s40, s66, s47
	v_lshl_add_u64 v[160:161], v[160:161], 0, s[16:17]
	s_mov_b32 m0, s40
	ds_read_b128 v[184:187], v165 offset:49152
	ds_read_b128 v[188:191], v165 offset:50176
	ds_read_b128 v[192:195], v165 offset:51200
	ds_read_b128 v[196:199], v165 offset:52224
	ds_read_b128 v[200:203], v165 offset:53248
	ds_read_b128 v[204:207], v165 offset:54272
	ds_read_b128 v[208:211], v165 offset:55296
	ds_read_b128 v[212:215], v165 offset:56320
	global_load_lds_dwordx4 v[160:161], off
	s_add_i32 m0, s40, 0x2000
	s_add_u32 s38, s38, 0x40080
	v_lshl_add_u64 v[160:161], v[216:217], 0, s[16:17]
	s_addc_u32 s39, s39, 0
	s_add_i32 s40, s67, s47
	global_load_lds_dwordx4 v[160:161], off
	v_lshl_add_u64 v[160:161], s[38:39], 0, v[132:133]
	s_mov_b32 m0, s40
	s_nop 0
	global_load_lds_dwordx4 v[160:161], off
	v_lshl_add_u64 v[160:161], s[38:39], 0, v[128:129]
	s_add_i32 m0, s40, 0x2000
	s_nop 0
	global_load_lds_dwordx4 v[160:161], off
	v_lshl_add_u64 v[160:161], v[218:219], 0, s[16:17]
	s_mov_b32 m0, s57
	s_nop 0
	global_load_lds_dwordx4 v[160:161], off
	v_lshl_add_u64 v[160:161], v[220:221], 0, s[16:17]
	s_mov_b32 m0, s58
	s_nop 0
	global_load_lds_dwordx4 v[160:161], off
	s_waitcnt vmcnt(8)
	s_waitcnt lgkmcnt(0)
	s_barrier
	s_setprio 1
	s_waitcnt lgkmcnt(0)
	v_mfma_f32_16x16x32_bf16 v[60:63], v[144:147], v[184:187], v[60:63]
	s_cmp_lg_u32 s65, 12
	s_cbranch_scc1 .Lll_p6
	global_load_dword v224, v232, s[12:13]
	global_load_dword v225, v232, s[12:13] offset:64
	global_load_dword v226, v232, s[12:13] offset:128
	global_load_dword v227, v232, s[12:13] offset:192
	global_load_dword v228, v232, s[12:13] offset:512
	global_load_dword v229, v232, s[12:13] offset:576
	global_load_dword v230, v232, s[12:13] offset:640
	global_load_dword v231, v232, s[12:13] offset:704
.Lll_p6:
	v_mfma_f32_16x16x32_bf16 v[56:59], v[152:155], v[184:187], v[56:59]
	v_mfma_f32_16x16x32_bf16 v[44:47], v[144:147], v[192:195], v[44:47]
	v_mfma_f32_16x16x32_bf16 v[40:43], v[152:155], v[192:195], v[40:43]
	v_mfma_f32_16x16x32_bf16 v[28:31], v[144:147], v[200:203], v[28:31]
	v_mfma_f32_16x16x32_bf16 v[24:27], v[152:155], v[200:203], v[24:27]
	v_mfma_f32_16x16x32_bf16 v[12:15], v[144:147], v[208:211], v[12:15]
	v_mfma_f32_16x16x32_bf16 v[8:11], v[152:155], v[208:211], v[8:11]
	v_mfma_f32_16x16x32_bf16 v[60:63], v[148:151], v[188:191], v[60:63]
	v_mfma_f32_16x16x32_bf16 v[56:59], v[156:159], v[188:191], v[56:59]
	v_mfma_f32_16x16x32_bf16 v[44:47], v[148:151], v[196:199], v[44:47]
	v_mfma_f32_16x16x32_bf16 v[40:43], v[156:159], v[196:199], v[40:43]
	v_mfma_f32_16x16x32_bf16 v[28:31], v[148:151], v[204:207], v[28:31]
	v_mfma_f32_16x16x32_bf16 v[24:27], v[156:159], v[204:207], v[24:27]
	v_mfma_f32_16x16x32_bf16 v[12:15], v[148:151], v[212:215], v[12:15]
	v_mfma_f32_16x16x32_bf16 v[8:11], v[156:159], v[212:215], v[8:11]
	s_setprio 0
	s_setprio 1
	v_mfma_f32_16x16x32_bf16 v[52:55], v[168:171], v[184:187], v[52:55]
	v_mfma_f32_16x16x32_bf16 v[48:51], v[176:179], v[184:187], v[48:51]
	v_mfma_f32_16x16x32_bf16 v[36:39], v[168:171], v[192:195], v[36:39]
	v_mfma_f32_16x16x32_bf16 v[32:35], v[176:179], v[192:195], v[32:35]
	v_mfma_f32_16x16x32_bf16 v[20:23], v[168:171], v[200:203], v[20:23]
	v_mfma_f32_16x16x32_bf16 v[16:19], v[176:179], v[200:203], v[16:19]
	v_mfma_f32_16x16x32_bf16 v[4:7], v[168:171], v[208:211], v[4:7]
	v_mfma_f32_16x16x32_bf16 v[0:3], v[176:179], v[208:211], v[0:3]
	v_mfma_f32_16x16x32_bf16 v[52:55], v[172:175], v[188:191], v[52:55]
	v_mfma_f32_16x16x32_bf16 v[48:51], v[180:183], v[188:191], v[48:51]
	v_mfma_f32_16x16x32_bf16 v[36:39], v[172:175], v[196:199], v[36:39]
	v_mfma_f32_16x16x32_bf16 v[32:35], v[180:183], v[196:199], v[32:35]
	s_setprio 2
	s_barrier
	v_mfma_f32_16x16x32_bf16 v[20:23], v[172:175], v[204:207], v[20:23]
	v_mfma_f32_16x16x32_bf16 v[16:19], v[180:183], v[204:207], v[16:19]
	v_mfma_f32_16x16x32_bf16 v[4:7], v[172:175], v[212:215], v[4:7]
	v_mfma_f32_16x16x32_bf16 v[0:3], v[180:183], v[212:215], v[0:3]
	s_setprio 0
	s_add_i32 s65, s65, 2
	s_add_u32 s36, s36, 0x100
	s_addc_u32 s37, s37, 0
	s_add_u32 s63, s63, 0x100
	s_addc_u32 s64, s64, 0
	s_cmp_gt_u32 s65, 13
	s_cbranch_scc0 .LBB0_784
.LBB0_787:
	s_lshl_b32 s23, s30, 8
	s_add_i32 s23, s23, s56
	v_mbcnt_lo_u32_b32 v146, -1, 0
	v_mbcnt_hi_u32_b32 v146, -1, v146
	s_lshl_b32 s30, s21, 7
	v_and_or_b32 v148, v146, 15, s23
	v_ashrrev_i32_e32 v149, 31, v148
	v_lshl_add_u64 v[144:145], v[148:149], 2, s[12:13]
	v_or_b32_e32 v158, 16, v148
	v_ashrrev_i32_e32 v159, 31, v158
	v_lshl_add_u64 v[144:145], v[158:159], 2, s[12:13]
	v_ashrrev_i32_e32 v146, 1, v146
	v_mov_b64_e32 v[144:145], s[14:15]
	s_ashr_i32 s31, s30, 31
	v_and_b32_e32 v168, -8, v146
	v_or_b32_e32 v160, 32, v148
	s_lshl_b64 s[30:31], s[30:31], 1
	v_or_b32_e32 v156, 48, v148
	v_add_u32_e32 v154, 0x80, v148
	v_add_u32_e32 v152, 0x90, v148
	v_add_u32_e32 v150, 0xa0, v148
	v_add_u32_e32 v146, 0xb0, v148
	v_ashrrev_i32_e32 v169, 31, v168
	v_mad_i64_i32 v[148:149], s[36:37], v148, s61, v[144:145]
	v_ashrrev_i32_e32 v161, 31, v160
	v_ashrrev_i32_e32 v157, 31, v156
	v_ashrrev_i32_e32 v155, 31, v154
	v_ashrrev_i32_e32 v153, 31, v152
	v_ashrrev_i32_e32 v151, 31, v150
	v_ashrrev_i32_e32 v147, 31, v146
	v_lshl_add_u64 v[170:171], v[148:149], 0, s[30:31]
	v_lshlrev_b64 v[148:149], 1, v[168:169]
	v_lshl_add_u64 v[168:169], v[160:161], 2, s[12:13]
	v_lshl_add_u64 v[172:173], v[156:157], 2, s[12:13]
	v_lshl_add_u64 v[174:175], v[154:155], 2, s[12:13]
	v_lshl_add_u64 v[176:177], v[152:153], 2, s[12:13]
	v_lshl_add_u64 v[178:179], v[150:151], 2, s[12:13]
	v_lshl_add_u64 v[180:181], v[146:147], 2, s[12:13]
	s_mov_b32 s21, s7
	v_lshl_add_u64 v[170:171], v[170:171], 0, s[20:21]
	v_lshl_add_u64 v[170:171], v[170:171], 0, v[148:149]
	s_andn2_b64 vcc, exec, s[4:5]
	s_mov_b64 s[4:5], -1
	s_cmp_eq_u64 s[18:19], 0
	s_cbranch_scc1 .Lalign_1
	s_barrier
.Lalign_1:
	s_waitcnt vmcnt(0)
	v_mov_b32_e32 v167, v224
	v_mov_b32_e32 v159, v225
	v_mov_b32_e32 v153, v226
	v_mov_b32_e32 v155, v227
	v_mov_b32_e32 v157, v228
	v_mov_b32_e32 v161, v229
	v_mov_b32_e32 v151, v230
	v_mov_b32_e32 v147, v231
	v_fmamk_f32 v167, v167, 0x3a800000, v166
	v_rsq_f32_e32 v168, v167
	v_fmamk_f32 v159, v159, 0x3a800000, v166
	v_pk_mul_f32 v[124:125], v[124:125], v[168:169] op_sel_hi:[1,0]
	v_pk_mul_f32 v[126:127], v[126:127], v[168:169] op_sel_hi:[1,0]
	v_pk_mul_f32 v[120:121], v[120:121], v[168:169] op_sel_hi:[1,0]
	v_pk_mul_f32 v[122:123], v[122:123], v[168:169] op_sel_hi:[1,0]
	v_rsq_f32_e32 v172, v159
	v_pk_mul_f32 v[116:117], v[116:117], v[168:169] op_sel_hi:[1,0]
	v_pk_mul_f32 v[118:119], v[118:119], v[168:169] op_sel_hi:[1,0]
	v_pk_mul_f32 v[112:113], v[112:113], v[168:169] op_sel_hi:[1,0]
	v_pk_mul_f32 v[114:115], v[114:115], v[168:169] op_sel_hi:[1,0]
	v_mul_f32_e32 v159, 0xbfb8aa3b, v124
	v_mul_f32_e32 v167, 0xbfb8aa3b, v125
	v_mul_f32_e32 v168, 0xbfb8aa3b, v126
	v_mul_f32_e32 v169, 0xbfb8aa3b, v127
	v_mul_f32_e32 v173, 0xbfb8aa3b, v120
	v_mul_f32_e32 v174, 0xbfb8aa3b, v121
	v_mul_f32_e32 v175, 0xbfb8aa3b, v122
	v_mul_f32_e32 v176, 0xbfb8aa3b, v123
	v_exp_f32_e32 v159, v159
	v_exp_f32_e32 v167, v167
	v_exp_f32_e32 v168, v168
	v_exp_f32_e32 v169, v169
	v_exp_f32_e32 v173, v173
	v_exp_f32_e32 v174, v174
	v_exp_f32_e32 v175, v175
	v_exp_f32_e32 v176, v176
	v_add_f32_e32 v159, 1.0, v159
	v_add_f32_e32 v167, 1.0, v167
	v_add_f32_e32 v177, 1.0, v168
	v_add_f32_e32 v178, 1.0, v169
	v_add_f32_e32 v173, 1.0, v173
	v_add_f32_e32 v179, 1.0, v174
	v_add_f32_e32 v180, 1.0, v175
	v_add_f32_e32 v181, 1.0, v176
	v_rcp_f32_e32 v168, v159
	v_rcp_f32_e32 v169, v167
	v_rcp_f32_e32 v174, v177
	v_rcp_f32_e32 v175, v178
	v_rcp_f32_e32 v176, v173
	v_rcp_f32_e32 v177, v179
	v_rcp_f32_e32 v178, v180
	v_rcp_f32_e32 v179, v181
	v_pk_mul_f32 v[124:125], v[124:125], v[168:169]
	v_pk_mul_f32 v[126:127], v[126:127], v[174:175]
	v_pk_mul_f32 v[120:121], v[120:121], v[176:177]
	v_pk_mul_f32 v[122:123], v[122:123], v[178:179]
	v_pk_mul_f32 v[116:117], v[116:117], v[124:125]
	v_pk_mul_f32 v[118:119], v[118:119], v[126:127]
	v_pk_mul_f32 v[120:121], v[112:113], v[120:121]
	v_pk_mul_f32 v[122:123], v[114:115], v[122:123]
	v_cvt_pk_bf16_f32 v112, v116, v117
	v_cvt_pk_bf16_f32 v113, v118, v119
	v_cvt_pk_bf16_f32 v114, v120, v121
	v_cvt_pk_bf16_f32 v115, v122, v123
	v_pk_mul_f32 v[108:109], v[108:109], v[172:173] op_sel_hi:[1,0]
	global_store_dwordx4 v[170:171], v[112:115], off
	v_mul_f32_e32 v116, 0xbfb8aa3b, v108
	v_pk_mul_f32 v[110:111], v[110:111], v[172:173] op_sel_hi:[1,0]
	v_mul_f32_e32 v112, 0xbfb8aa3b, v109
	v_exp_f32_e32 v116, v116
	v_exp_f32_e32 v113, v112
	v_mul_f32_e32 v114, 0xbfb8aa3b, v110
	v_mul_f32_e32 v115, 0xbfb8aa3b, v111
	v_exp_f32_e32 v114, v114
	v_exp_f32_e32 v115, v115
	v_add_f32_e32 v112, 1.0, v116
	v_add_f32_e32 v113, 1.0, v113
	v_rcp_f32_e32 v112, v112
	v_rcp_f32_e32 v113, v113
	v_add_f32_e32 v114, 1.0, v114
	v_add_f32_e32 v115, 1.0, v115
	v_rcp_f32_e32 v114, v114
	v_rcp_f32_e32 v115, v115
	v_pk_mul_f32 v[100:101], v[100:101], v[172:173] op_sel_hi:[1,0]
	v_pk_mul_f32 v[108:109], v[108:109], v[112:113]
	v_pk_mul_f32 v[104:105], v[104:105], v[172:173] op_sel_hi:[1,0]
	v_pk_mul_f32 v[100:101], v[100:101], v[108:109]
	v_pk_mul_f32 v[108:109], v[110:111], v[114:115]
	v_mul_f32_e32 v110, 0xbfb8aa3b, v104
	v_exp_f32_e32 v110, v110
	v_pk_mul_f32 v[102:103], v[102:103], v[172:173] op_sel_hi:[1,0]
	v_pk_mul_f32 v[106:107], v[106:107], v[172:173] op_sel_hi:[1,0]
	v_pk_mul_f32 v[102:103], v[102:103], v[108:109]
	v_mul_f32_e32 v108, 0xbfb8aa3b, v105
	v_exp_f32_e32 v109, v108
	v_add_f32_e32 v108, 1.0, v110
	v_mul_f32_e32 v110, 0xbfb8aa3b, v106
	v_mul_f32_e32 v111, 0xbfb8aa3b, v107
	v_exp_f32_e32 v110, v110
	v_exp_f32_e32 v111, v111
	v_add_f32_e32 v109, 1.0, v109
	v_rcp_f32_e32 v108, v108
	v_rcp_f32_e32 v109, v109
	v_add_f32_e32 v110, 1.0, v110
	v_add_f32_e32 v111, 1.0, v111
	v_rcp_f32_e32 v110, v110
	v_rcp_f32_e32 v111, v111
	v_pk_mul_f32 v[96:97], v[96:97], v[172:173] op_sel_hi:[1,0]
	v_pk_mul_f32 v[104:105], v[104:105], v[108:109]
	s_nop 0
	v_pk_mul_f32 v[104:105], v[96:97], v[104:105]
	v_pk_mul_f32 v[96:97], v[98:99], v[172:173] op_sel_hi:[1,0]
	v_pk_mul_f32 v[98:99], v[106:107], v[110:111]
	s_nop 0
	v_pk_mul_f32 v[106:107], v[96:97], v[98:99]
	v_mad_i64_i32 v[96:97], s[36:37], v158, s61, v[144:145]
	v_lshl_add_u64 v[96:97], v[96:97], 0, s[30:31]
	v_lshl_add_u64 v[96:97], v[96:97], 0, s[20:21]
	v_lshl_add_u64 v[108:109], v[96:97], 0, v[148:149]
	v_fmamk_f32 v97, v153, 0x3a800000, v166
	v_cvt_pk_bf16_f32 v96, v100, v101
	v_rsq_f32_e32 v100, v97
	v_cvt_pk_bf16_f32 v97, v102, v103
	v_cvt_pk_bf16_f32 v98, v104, v105
	v_cvt_pk_bf16_f32 v99, v106, v107
	v_pk_mul_f32 v[92:93], v[92:93], v[100:101] op_sel_hi:[1,0]
	global_store_dwordx4 v[108:109], v[96:99], off
	v_mul_f32_e32 v101, 0xbfb8aa3b, v92
	v_exp_f32_e32 v101, v101
	v_mul_f32_e32 v96, 0xbfb8aa3b, v93
	v_exp_f32_e32 v97, v96
	v_pk_mul_f32 v[94:95], v[94:95], v[100:101] op_sel_hi:[1,0]
	s_nop 0
	v_mul_f32_e32 v98, 0xbfb8aa3b, v94
	v_mul_f32_e32 v99, 0xbfb8aa3b, v95
	v_exp_f32_e32 v98, v98
	v_exp_f32_e32 v99, v99
	v_add_f32_e32 v96, 1.0, v101
	v_add_f32_e32 v97, 1.0, v97
	v_rcp_f32_e32 v96, v96
	v_rcp_f32_e32 v97, v97
	v_add_f32_e32 v98, 1.0, v98
	v_add_f32_e32 v99, 1.0, v99
	v_rcp_f32_e32 v98, v98
	v_rcp_f32_e32 v99, v99
	v_pk_mul_f32 v[84:85], v[84:85], v[100:101] op_sel_hi:[1,0]
	v_pk_mul_f32 v[92:93], v[92:93], v[96:97]
	v_pk_mul_f32 v[88:89], v[88:89], v[100:101] op_sel_hi:[1,0]
	v_pk_mul_f32 v[84:85], v[84:85], v[92:93]
	v_pk_mul_f32 v[92:93], v[94:95], v[98:99]
	v_mul_f32_e32 v94, 0xbfb8aa3b, v88
	v_exp_f32_e32 v94, v94
	v_pk_mul_f32 v[86:87], v[86:87], v[100:101] op_sel_hi:[1,0]
	v_pk_mul_f32 v[90:91], v[90:91], v[100:101] op_sel_hi:[1,0]
	v_pk_mul_f32 v[86:87], v[86:87], v[92:93]
	v_mul_f32_e32 v92, 0xbfb8aa3b, v89
	v_exp_f32_e32 v93, v92
	v_add_f32_e32 v92, 1.0, v94
	v_mul_f32_e32 v94, 0xbfb8aa3b, v90
	v_mul_f32_e32 v95, 0xbfb8aa3b, v91
	v_exp_f32_e32 v94, v94
	v_exp_f32_e32 v95, v95
	v_add_f32_e32 v93, 1.0, v93
	v_rcp_f32_e32 v92, v92
	v_rcp_f32_e32 v93, v93
	v_add_f32_e32 v94, 1.0, v94
	v_add_f32_e32 v95, 1.0, v95
	v_rcp_f32_e32 v94, v94
	v_rcp_f32_e32 v95, v95
	v_pk_mul_f32 v[80:81], v[80:81], v[100:101] op_sel_hi:[1,0]
	v_pk_mul_f32 v[88:89], v[88:89], v[92:93]
	s_nop 0
	v_pk_mul_f32 v[88:89], v[80:81], v[88:89]
	v_pk_mul_f32 v[80:81], v[82:83], v[100:101] op_sel_hi:[1,0]
	v_pk_mul_f32 v[82:83], v[90:91], v[94:95]
	s_nop 0
	v_pk_mul_f32 v[90:91], v[80:81], v[82:83]
	v_mad_i64_i32 v[80:81], s[36:37], v160, s61, v[144:145]
	v_lshl_add_u64 v[80:81], v[80:81], 0, s[30:31]
	v_lshl_add_u64 v[80:81], v[80:81], 0, s[20:21]
	v_lshl_add_u64 v[92:93], v[80:81], 0, v[148:149]
	v_fmamk_f32 v81, v155, 0x3a800000, v166
	v_cvt_pk_bf16_f32 v80, v84, v85
	v_rsq_f32_e32 v84, v81
	v_cvt_pk_bf16_f32 v81, v86, v87
	v_cvt_pk_bf16_f32 v82, v88, v89
	v_cvt_pk_bf16_f32 v83, v90, v91
	v_pk_mul_f32 v[76:77], v[76:77], v[84:85] op_sel_hi:[1,0]
	global_store_dwordx4 v[92:93], v[80:83], off
	v_mul_f32_e32 v85, 0xbfb8aa3b, v76
	v_exp_f32_e32 v85, v85
	v_mul_f32_e32 v80, 0xbfb8aa3b, v77
	v_exp_f32_e32 v81, v80
	v_pk_mul_f32 v[78:79], v[78:79], v[84:85] op_sel_hi:[1,0]
	s_nop 0
	v_mul_f32_e32 v82, 0xbfb8aa3b, v78
	v_mul_f32_e32 v83, 0xbfb8aa3b, v79
	v_exp_f32_e32 v82, v82
	v_exp_f32_e32 v83, v83
	v_add_f32_e32 v80, 1.0, v85
	v_add_f32_e32 v81, 1.0, v81
	v_rcp_f32_e32 v80, v80
	v_rcp_f32_e32 v81, v81
	v_add_f32_e32 v82, 1.0, v82
	v_add_f32_e32 v83, 1.0, v83
	v_rcp_f32_e32 v82, v82
	v_rcp_f32_e32 v83, v83
	v_pk_mul_f32 v[68:69], v[68:69], v[84:85] op_sel_hi:[1,0]
	v_pk_mul_f32 v[76:77], v[76:77], v[80:81]
	v_pk_mul_f32 v[72:73], v[72:73], v[84:85] op_sel_hi:[1,0]
	v_pk_mul_f32 v[68:69], v[68:69], v[76:77]
	v_pk_mul_f32 v[76:77], v[78:79], v[82:83]
	v_mul_f32_e32 v78, 0xbfb8aa3b, v72
	v_exp_f32_e32 v78, v78
	v_pk_mul_f32 v[70:71], v[70:71], v[84:85] op_sel_hi:[1,0]
	v_pk_mul_f32 v[74:75], v[74:75], v[84:85] op_sel_hi:[1,0]
	v_pk_mul_f32 v[70:71], v[70:71], v[76:77]
	v_mul_f32_e32 v76, 0xbfb8aa3b, v73
	v_exp_f32_e32 v77, v76
	v_add_f32_e32 v76, 1.0, v78
	v_mul_f32_e32 v78, 0xbfb8aa3b, v74
	v_mul_f32_e32 v79, 0xbfb8aa3b, v75
	v_exp_f32_e32 v78, v78
	v_exp_f32_e32 v79, v79
	v_add_f32_e32 v77, 1.0, v77
	v_rcp_f32_e32 v76, v76
	v_rcp_f32_e32 v77, v77
	v_add_f32_e32 v78, 1.0, v78
	v_add_f32_e32 v79, 1.0, v79
	v_rcp_f32_e32 v78, v78
	v_rcp_f32_e32 v79, v79
	v_pk_mul_f32 v[64:65], v[64:65], v[84:85] op_sel_hi:[1,0]
	v_pk_mul_f32 v[72:73], v[72:73], v[76:77]
	s_nop 0
	v_pk_mul_f32 v[72:73], v[64:65], v[72:73]
	v_pk_mul_f32 v[64:65], v[66:67], v[84:85] op_sel_hi:[1,0]
	v_pk_mul_f32 v[66:67], v[74:75], v[78:79]
	s_nop 0
	v_pk_mul_f32 v[74:75], v[64:65], v[66:67]
	v_mad_i64_i32 v[64:65], s[36:37], v156, s61, v[144:145]
	v_lshl_add_u64 v[64:65], v[64:65], 0, s[30:31]
	v_lshl_add_u64 v[64:65], v[64:65], 0, s[20:21]
	v_fmamk_f32 v66, v157, 0x3a800000, v166
	v_lshl_add_u64 v[76:77], v[64:65], 0, v[148:149]
	v_cvt_pk_bf16_f32 v64, v68, v69
	v_rsq_f32_e32 v68, v66
	v_cvt_pk_bf16_f32 v65, v70, v71
	v_cvt_pk_bf16_f32 v66, v72, v73
	v_cvt_pk_bf16_f32 v67, v74, v75
	v_pk_mul_f32 v[60:61], v[60:61], v[68:69] op_sel_hi:[1,0]
	global_store_dwordx4 v[76:77], v[64:67], off
	v_pk_mul_f32 v[62:63], v[62:63], v[68:69] op_sel_hi:[1,0]
	v_pk_mul_f32 v[52:53], v[52:53], v[68:69] op_sel_hi:[1,0]
	v_mul_f32_e32 v64, 0xbfb8aa3b, v60
	v_mul_f32_e32 v65, 0xbfb8aa3b, v61
	v_exp_f32_e32 v64, v64
	v_exp_f32_e32 v65, v65
	v_mul_f32_e32 v66, 0xbfb8aa3b, v62
	v_mul_f32_e32 v67, 0xbfb8aa3b, v63
	v_exp_f32_e32 v66, v66
	v_exp_f32_e32 v67, v67
	v_add_f32_e32 v64, 1.0, v64
	v_add_f32_e32 v65, 1.0, v65
	v_rcp_f32_e32 v64, v64
	v_rcp_f32_e32 v65, v65
	v_add_f32_e32 v66, 1.0, v66
	v_add_f32_e32 v67, 1.0, v67
	v_rcp_f32_e32 v66, v66
	v_rcp_f32_e32 v67, v67
	v_pk_mul_f32 v[60:61], v[60:61], v[64:65]
	v_pk_mul_f32 v[56:57], v[56:57], v[68:69] op_sel_hi:[1,0]
	v_pk_mul_f32 v[52:53], v[52:53], v[60:61]
	v_pk_mul_f32 v[60:61], v[62:63], v[66:67]
	v_mul_f32_e32 v62, 0xbfb8aa3b, v56
	v_exp_f32_e32 v62, v62
	v_pk_mul_f32 v[54:55], v[54:55], v[68:69] op_sel_hi:[1,0]
	v_pk_mul_f32 v[58:59], v[58:59], v[68:69] op_sel_hi:[1,0]
	v_pk_mul_f32 v[54:55], v[54:55], v[60:61]
	v_mul_f32_e32 v60, 0xbfb8aa3b, v57
	v_exp_f32_e32 v61, v60
	v_add_f32_e32 v60, 1.0, v62
	v_mul_f32_e32 v62, 0xbfb8aa3b, v58
	v_mul_f32_e32 v63, 0xbfb8aa3b, v59
	v_exp_f32_e32 v62, v62
	v_exp_f32_e32 v63, v63
	v_add_f32_e32 v61, 1.0, v61
	v_rcp_f32_e32 v60, v60
	v_rcp_f32_e32 v61, v61
	v_add_f32_e32 v62, 1.0, v62
	v_add_f32_e32 v63, 1.0, v63
	v_rcp_f32_e32 v62, v62
	v_rcp_f32_e32 v63, v63
	v_pk_mul_f32 v[48:49], v[48:49], v[68:69] op_sel_hi:[1,0]
	v_pk_mul_f32 v[56:57], v[56:57], v[60:61]
	s_nop 0
	v_pk_mul_f32 v[56:57], v[48:49], v[56:57]
	v_pk_mul_f32 v[48:49], v[50:51], v[68:69] op_sel_hi:[1,0]
	v_pk_mul_f32 v[50:51], v[58:59], v[62:63]
	s_nop 0
	v_pk_mul_f32 v[58:59], v[48:49], v[50:51]
	v_mad_i64_i32 v[48:49], s[36:37], v154, s61, v[144:145]
	v_lshl_add_u64 v[48:49], v[48:49], 0, s[30:31]
	v_lshl_add_u64 v[48:49], v[48:49], 0, s[20:21]
	v_lshl_add_u64 v[60:61], v[48:49], 0, v[148:149]
	v_fmamk_f32 v49, v161, 0x3a800000, v166
	v_cvt_pk_bf16_f32 v48, v52, v53
	v_rsq_f32_e32 v52, v49
	v_cvt_pk_bf16_f32 v49, v54, v55
	v_cvt_pk_bf16_f32 v50, v56, v57
	v_cvt_pk_bf16_f32 v51, v58, v59
	v_pk_mul_f32 v[44:45], v[44:45], v[52:53] op_sel_hi:[1,0]
	global_store_dwordx4 v[60:61], v[48:51], off
	v_mul_f32_e32 v53, 0xbfb8aa3b, v44
	v_exp_f32_e32 v53, v53
	v_mul_f32_e32 v48, 0xbfb8aa3b, v45
	v_exp_f32_e32 v49, v48
	v_pk_mul_f32 v[46:47], v[46:47], v[52:53] op_sel_hi:[1,0]
	s_nop 0
	v_mul_f32_e32 v50, 0xbfb8aa3b, v46
	v_mul_f32_e32 v51, 0xbfb8aa3b, v47
	v_exp_f32_e32 v50, v50
	v_exp_f32_e32 v51, v51
	v_add_f32_e32 v48, 1.0, v53
	v_add_f32_e32 v49, 1.0, v49
	v_rcp_f32_e32 v48, v48
	v_rcp_f32_e32 v49, v49
	v_add_f32_e32 v50, 1.0, v50
	v_add_f32_e32 v51, 1.0, v51
	v_rcp_f32_e32 v50, v50
	v_rcp_f32_e32 v51, v51
	v_pk_mul_f32 v[36:37], v[36:37], v[52:53] op_sel_hi:[1,0]
	v_pk_mul_f32 v[44:45], v[44:45], v[48:49]
	v_pk_mul_f32 v[40:41], v[40:41], v[52:53] op_sel_hi:[1,0]
	v_pk_mul_f32 v[36:37], v[36:37], v[44:45]
	v_pk_mul_f32 v[44:45], v[46:47], v[50:51]
	v_mul_f32_e32 v46, 0xbfb8aa3b, v40
	v_exp_f32_e32 v46, v46
	v_pk_mul_f32 v[38:39], v[38:39], v[52:53] op_sel_hi:[1,0]
	v_pk_mul_f32 v[42:43], v[42:43], v[52:53] op_sel_hi:[1,0]
	v_pk_mul_f32 v[38:39], v[38:39], v[44:45]
	v_mul_f32_e32 v44, 0xbfb8aa3b, v41
	v_exp_f32_e32 v45, v44
	v_add_f32_e32 v44, 1.0, v46
	v_mul_f32_e32 v46, 0xbfb8aa3b, v42
	v_mul_f32_e32 v47, 0xbfb8aa3b, v43
	v_exp_f32_e32 v46, v46
	v_exp_f32_e32 v47, v47
	v_add_f32_e32 v45, 1.0, v45
	v_rcp_f32_e32 v44, v44
	v_rcp_f32_e32 v45, v45
	v_add_f32_e32 v46, 1.0, v46
	v_add_f32_e32 v47, 1.0, v47
	v_rcp_f32_e32 v46, v46
	v_rcp_f32_e32 v47, v47
	v_pk_mul_f32 v[32:33], v[32:33], v[52:53] op_sel_hi:[1,0]
	v_pk_mul_f32 v[40:41], v[40:41], v[44:45]
	s_nop 0
	v_pk_mul_f32 v[40:41], v[32:33], v[40:41]
	v_pk_mul_f32 v[32:33], v[34:35], v[52:53] op_sel_hi:[1,0]
	v_pk_mul_f32 v[34:35], v[42:43], v[46:47]
	s_nop 0
	v_pk_mul_f32 v[42:43], v[32:33], v[34:35]
	v_mad_i64_i32 v[32:33], s[36:37], v152, s61, v[144:145]
	v_lshl_add_u64 v[32:33], v[32:33], 0, s[30:31]
	v_lshl_add_u64 v[32:33], v[32:33], 0, s[20:21]
	v_lshl_add_u64 v[44:45], v[32:33], 0, v[148:149]
	v_fmamk_f32 v33, v151, 0x3a800000, v166
	v_cvt_pk_bf16_f32 v32, v36, v37
	v_rsq_f32_e32 v36, v33
	v_cvt_pk_bf16_f32 v33, v38, v39
	v_cvt_pk_bf16_f32 v34, v40, v41
	v_cvt_pk_bf16_f32 v35, v42, v43
	v_pk_mul_f32 v[28:29], v[28:29], v[36:37] op_sel_hi:[1,0]
	global_store_dwordx4 v[44:45], v[32:35], off
	v_mul_f32_e32 v37, 0xbfb8aa3b, v28
	v_exp_f32_e32 v37, v37
	v_mul_f32_e32 v32, 0xbfb8aa3b, v29
	v_exp_f32_e32 v33, v32
	v_pk_mul_f32 v[30:31], v[30:31], v[36:37] op_sel_hi:[1,0]
	s_nop 0
	v_mul_f32_e32 v34, 0xbfb8aa3b, v30
	v_mul_f32_e32 v35, 0xbfb8aa3b, v31
	v_exp_f32_e32 v34, v34
	v_exp_f32_e32 v35, v35
	v_add_f32_e32 v32, 1.0, v37
	v_add_f32_e32 v33, 1.0, v33
	v_rcp_f32_e32 v32, v32
	v_rcp_f32_e32 v33, v33
	v_add_f32_e32 v34, 1.0, v34
	v_add_f32_e32 v35, 1.0, v35
	v_rcp_f32_e32 v34, v34
	v_rcp_f32_e32 v35, v35
	v_pk_mul_f32 v[20:21], v[20:21], v[36:37] op_sel_hi:[1,0]
	v_pk_mul_f32 v[28:29], v[28:29], v[32:33]
	v_pk_mul_f32 v[24:25], v[24:25], v[36:37] op_sel_hi:[1,0]
	v_pk_mul_f32 v[20:21], v[20:21], v[28:29]
	v_pk_mul_f32 v[28:29], v[30:31], v[34:35]
	v_mul_f32_e32 v30, 0xbfb8aa3b, v24
	v_exp_f32_e32 v30, v30
	v_pk_mul_f32 v[22:23], v[22:23], v[36:37] op_sel_hi:[1,0]
	v_pk_mul_f32 v[26:27], v[26:27], v[36:37] op_sel_hi:[1,0]
	v_pk_mul_f32 v[22:23], v[22:23], v[28:29]
	v_mul_f32_e32 v28, 0xbfb8aa3b, v25
	v_exp_f32_e32 v29, v28
	v_add_f32_e32 v28, 1.0, v30
	v_mul_f32_e32 v30, 0xbfb8aa3b, v26
	v_mul_f32_e32 v31, 0xbfb8aa3b, v27
	v_exp_f32_e32 v30, v30
	v_exp_f32_e32 v31, v31
	v_add_f32_e32 v29, 1.0, v29
	v_rcp_f32_e32 v28, v28
	v_rcp_f32_e32 v29, v29
	v_add_f32_e32 v30, 1.0, v30
	v_add_f32_e32 v31, 1.0, v31
	v_rcp_f32_e32 v30, v30
	v_rcp_f32_e32 v31, v31
	v_pk_mul_f32 v[16:17], v[16:17], v[36:37] op_sel_hi:[1,0]
	v_pk_mul_f32 v[24:25], v[24:25], v[28:29]
	s_nop 0
	v_pk_mul_f32 v[24:25], v[16:17], v[24:25]
	v_pk_mul_f32 v[16:17], v[18:19], v[36:37] op_sel_hi:[1,0]
	v_pk_mul_f32 v[18:19], v[26:27], v[30:31]
	s_nop 0
	v_pk_mul_f32 v[26:27], v[16:17], v[18:19]
	v_mad_i64_i32 v[16:17], s[36:37], v150, s61, v[144:145]
	v_lshl_add_u64 v[16:17], v[16:17], 0, s[30:31]
	v_lshl_add_u64 v[16:17], v[16:17], 0, s[20:21]
	v_lshl_add_u64 v[28:29], v[16:17], 0, v[148:149]
	v_fmamk_f32 v17, v147, 0x3a800000, v166
	v_cvt_pk_bf16_f32 v16, v20, v21
	v_rsq_f32_e32 v20, v17
	v_cvt_pk_bf16_f32 v17, v22, v23
	v_cvt_pk_bf16_f32 v18, v24, v25
	v_cvt_pk_bf16_f32 v19, v26, v27
	v_pk_mul_f32 v[12:13], v[12:13], v[20:21] op_sel_hi:[1,0]
	global_store_dwordx4 v[28:29], v[16:19], off
	v_mul_f32_e32 v21, 0xbfb8aa3b, v12
	v_exp_f32_e32 v21, v21
	v_mul_f32_e32 v16, 0xbfb8aa3b, v13
	v_exp_f32_e32 v17, v16
	v_pk_mul_f32 v[14:15], v[14:15], v[20:21] op_sel_hi:[1,0]
	s_nop 0
	v_mul_f32_e32 v18, 0xbfb8aa3b, v14
	v_mul_f32_e32 v19, 0xbfb8aa3b, v15
	v_exp_f32_e32 v18, v18
	v_exp_f32_e32 v19, v19
	v_add_f32_e32 v16, 1.0, v21
	v_add_f32_e32 v17, 1.0, v17
	v_rcp_f32_e32 v16, v16
	v_rcp_f32_e32 v17, v17
	v_add_f32_e32 v18, 1.0, v18
	v_add_f32_e32 v19, 1.0, v19
	v_rcp_f32_e32 v18, v18
	v_rcp_f32_e32 v19, v19
	v_pk_mul_f32 v[4:5], v[4:5], v[20:21] op_sel_hi:[1,0]
	v_pk_mul_f32 v[12:13], v[12:13], v[16:17]
	v_pk_mul_f32 v[8:9], v[8:9], v[20:21] op_sel_hi:[1,0]
	v_pk_mul_f32 v[4:5], v[4:5], v[12:13]
	v_pk_mul_f32 v[12:13], v[14:15], v[18:19]
	v_mul_f32_e32 v14, 0xbfb8aa3b, v8
	v_exp_f32_e32 v14, v14
	v_pk_mul_f32 v[6:7], v[6:7], v[20:21] op_sel_hi:[1,0]
	v_pk_mul_f32 v[10:11], v[10:11], v[20:21] op_sel_hi:[1,0]
	v_pk_mul_f32 v[6:7], v[6:7], v[12:13]
	v_mul_f32_e32 v12, 0xbfb8aa3b, v9
	v_exp_f32_e32 v13, v12
	v_add_f32_e32 v12, 1.0, v14
	v_mul_f32_e32 v14, 0xbfb8aa3b, v10
	v_mul_f32_e32 v15, 0xbfb8aa3b, v11
	v_exp_f32_e32 v14, v14
	v_exp_f32_e32 v15, v15
	v_add_f32_e32 v13, 1.0, v13
	v_rcp_f32_e32 v12, v12
	v_rcp_f32_e32 v13, v13
	v_add_f32_e32 v14, 1.0, v14
	v_add_f32_e32 v15, 1.0, v15
	v_rcp_f32_e32 v14, v14
	v_rcp_f32_e32 v15, v15
	v_pk_mul_f32 v[0:1], v[0:1], v[20:21] op_sel_hi:[1,0]
	v_pk_mul_f32 v[8:9], v[8:9], v[12:13]
	s_nop 0
	v_pk_mul_f32 v[8:9], v[0:1], v[8:9]
	v_pk_mul_f32 v[0:1], v[2:3], v[20:21] op_sel_hi:[1,0]
	v_pk_mul_f32 v[2:3], v[10:11], v[14:15]
	s_nop 0
	v_pk_mul_f32 v[10:11], v[0:1], v[2:3]
	v_mad_i64_i32 v[0:1], s[36:37], v146, s61, v[144:145]
	v_lshl_add_u64 v[0:1], v[0:1], 0, s[30:31]
	v_lshl_add_u64 v[0:1], v[0:1], 0, s[20:21]
	v_lshl_add_u64 v[12:13], v[0:1], 0, v[148:149]
	v_cvt_pk_bf16_f32 v0, v4, v5
	v_cvt_pk_bf16_f32 v1, v6, v7
	v_cvt_pk_bf16_f32 v2, v8, v9
	v_cvt_pk_bf16_f32 v3, v10, v11
	global_store_dwordx4 v[12:13], v[0:3], off
	s_cbranch_vccnz .LBB0_780
	s_andn2_b64 vcc, exec, s[8:9]
	s_cbranch_vccnz .LBB0_779
	s_barrier
	s_branch .LBB0_779
